# clique barrier at S5 gate->out too; L1 invalidate issued with the arrival (overlaps the wait) in clique barriers
# baseline (speedup 1.0000x reference)
; DEVI unsigned xb_ld(unsigned* p)              { return __hip_atomic_load(p, __ATOMIC_RELAXED, __HIP_MEMORY_SCOPE_AGENT); }
; DEVI unsigned xb_add(unsigned* p, unsigned v) { return __hip_atomic_fetch_add(p, v, __ATOMIC_RELAXED, __HIP_MEMORY_SCOPE_AGENT); }
; #define XB_SPIN(cond, bar) do { unsigned _sp = 0; while (cond) { __builtin_amdgcn_s_sleep(1); \
;     if ((++_sp & 255u) == 0u) { if (xb_ld(&(bar)[XB_TMO])) break; if (_sp > XB_SPIN_CAP) { atomicAdd(&(bar)[XB_TMO], 1u); break; } } } } while (0)
; DEVI void xcd_barrier(const XcdBarrier& b) {
;     asm volatile("s_waitcnt vmcnt(0)" ::: "memory");
;     __syncthreads();
;     if (threadIdx.x == 0) {
;         unsigned* bar = b.bar;
;         __builtin_amdgcn_s_waitcnt(0);
;         unsigned nloc = b.st[0], nx = b.st[1];
;         if (nloc == 0u) { xcd_barrier_complete(bar, b.x, nloc, nx); b.st[0] = nloc; b.st[1] = nx; }
;         const unsigned old = xb_add(&bar[XB_XSUB(b.x)], 1u);
;         const unsigned gen = old / nloc;
;         if (old + 1u == (gen + 1u) * nloc) {
;             __builtin_amdgcn_fence(__ATOMIC_RELEASE, "agent");
;             asm volatile("s_waitcnt vmcnt(0)" ::: "memory");
;             const unsigned og = xb_add(&bar[XB_TOP], 1u);
;             const unsigned tg = og / nx;
;             if (og + 1u == (tg + 1u) * nx) xb_add(&bar[XB_TOPGEN], 1u);
;             else XB_SPIN(xb_ld(&bar[XB_TOPGEN]) == tg, bar);
;             __builtin_amdgcn_fence(__ATOMIC_ACQUIRE, "agent");
;             xb_add(&bar[XB_XGEN(b.x)], 1u);
;             asm volatile("s_waitcnt vmcnt(0)" ::: "memory");
;         } else {
;             XB_SPIN(xb_ld(&bar[XB_XGEN(b.x)]) == gen, bar);
;             __builtin_amdgcn_fence(__ATOMIC_ACQUIRE, "agent");
;             asm volatile("s_waitcnt vmcnt(0)" ::: "memory");
;         }
;     }
;     __syncthreads();
; }
.LBB0_1351:
	s_waitcnt vmcnt(0)
	s_waitcnt lgkmcnt(0)
	s_barrier
	s_mov_b64 s[2:3], exec
	v_readlane_b32 s0, v251, 6
	v_readlane_b32 s1, v251, 7
	s_and_b64 s[0:1], s[2:3], s[0:1]
	s_mov_b64 exec, s[0:1]
	s_cbranch_execz .LBB0_1399
	v_mov_b32_e32 v1, 0x26008
	ds_read_b32 v1, v1
	s_bfe_u32 s4, s33, 0x30003
	s_lshl_b32 s4, s4, 5
	s_addk_i32 s4, 0x800
	s_mov_b32 s5, 0
	s_waitcnt lgkmcnt(0)
	v_readfirstlane_b32 s6, v1
	v_lshl_add_u64 v[0:1], v[156:157], 0, s[4:5]
	v_mov_b32_e32 v2, 1
	s_cmp_eq_u32 s6, 0
	s_cbranch_scc1 .Lxq_slow_0
	global_atomic_add v3, v[0:1], v2, off sc0
	buffer_inv sc1
	s_mov_b32 s7, 0
	s_waitcnt vmcnt(0)
	v_or_b32_e32 v3, 3, v3
	v_add_u32_e32 v3, 1, v3

; DEVI unsigned xb_ld(unsigned* p)              { return __hip_atomic_load(p, __ATOMIC_RELAXED, __HIP_MEMORY_SCOPE_AGENT); }
; DEVI unsigned xb_add(unsigned* p, unsigned v) { return __hip_atomic_fetch_add(p, v, __ATOMIC_RELAXED, __HIP_MEMORY_SCOPE_AGENT); }
; #define XB_SPIN(cond, bar) do { unsigned _sp = 0; while (cond) { __builtin_amdgcn_s_sleep(1); \
;     if ((++_sp & 255u) == 0u) { if (xb_ld(&(bar)[XB_TMO])) break; if (_sp > XB_SPIN_CAP) { atomicAdd(&(bar)[XB_TMO], 1u); break; } } } } while (0)
; DEVI void xcd_barrier(const XcdBarrier& b) {
;     ...
;             __builtin_amdgcn_fence(__ATOMIC_ACQUIRE, "agent");
;             xb_add(&bar[XB_XGEN(b.x)], 1u);
;             asm volatile("s_waitcnt vmcnt(0)" ::: "memory");
;         } else {
;             XB_SPIN(xb_ld(&bar[XB_XGEN(b.x)]) == gen, bar);
;             __builtin_amdgcn_fence(__ATOMIC_ACQUIRE, "agent");
;             asm volatile("s_waitcnt vmcnt(0)" ::: "memory");
;         }
;     }
;     __syncthreads();
; }
.Lxq_done_0:
	s_branch .LBB0_1399

; DEVI unsigned xb_ld(unsigned* p)              { return __hip_atomic_load(p, __ATOMIC_RELAXED, __HIP_MEMORY_SCOPE_AGENT); }
; DEVI unsigned xb_add(unsigned* p, unsigned v) { return __hip_atomic_fetch_add(p, v, __ATOMIC_RELAXED, __HIP_MEMORY_SCOPE_AGENT); }
; #define XB_SPIN(cond, bar) do { unsigned _sp = 0; while (cond) { __builtin_amdgcn_s_sleep(1); \
;     if ((++_sp & 255u) == 0u) { if (xb_ld(&(bar)[XB_TMO])) break; if (_sp > XB_SPIN_CAP) { atomicAdd(&(bar)[XB_TMO], 1u); break; } } } } while (0)
; DEVI void xcd_barrier(const XcdBarrier& b) {
;     asm volatile("s_waitcnt vmcnt(0)" ::: "memory");
;     __syncthreads();
;     if (threadIdx.x == 0) {
;         unsigned* bar = b.bar;
;         __builtin_amdgcn_s_waitcnt(0);
;         unsigned nloc = b.st[0], nx = b.st[1];
;         if (nloc == 0u) { xcd_barrier_complete(bar, b.x, nloc, nx); b.st[0] = nloc; b.st[1] = nx; }
;         const unsigned old = xb_add(&bar[XB_XSUB(b.x)], 1u);
;         const unsigned gen = old / nloc;
;         if (old + 1u == (gen + 1u) * nloc) {
;             __builtin_amdgcn_fence(__ATOMIC_RELEASE, "agent");
;             asm volatile("s_waitcnt vmcnt(0)" ::: "memory");
;             const unsigned og = xb_add(&bar[XB_TOP], 1u);
;             const unsigned tg = og / nx;
;             if (og + 1u == (tg + 1u) * nx) xb_add(&bar[XB_TOPGEN], 1u);
;             else XB_SPIN(xb_ld(&bar[XB_TOPGEN]) == tg, bar);
;             __builtin_amdgcn_fence(__ATOMIC_ACQUIRE, "agent");
;             xb_add(&bar[XB_XGEN(b.x)], 1u);
;             asm volatile("s_waitcnt vmcnt(0)" ::: "memory");
;         } else {
;             XB_SPIN(xb_ld(&bar[XB_XGEN(b.x)]) == gen, bar);
;             __builtin_amdgcn_fence(__ATOMIC_ACQUIRE, "agent");
;             asm volatile("s_waitcnt vmcnt(0)" ::: "memory");
;         }
;     }
;     __syncthreads();
; }
.LBB0_1439:
	s_waitcnt vmcnt(0)
	s_waitcnt lgkmcnt(0)
	s_barrier
	s_mov_b64 s[2:3], exec
	v_readlane_b32 s0, v251, 6
	v_readlane_b32 s1, v251, 7
	s_and_b64 s[0:1], s[2:3], s[0:1]
	s_mov_b64 exec, s[0:1]
	s_cbranch_execz .LBB0_1487
	v_mov_b32_e32 v1, 0x26008
	ds_read_b32 v1, v1
	s_bfe_u32 s4, s33, 0x30003
	s_lshl_b32 s4, s4, 5
	s_addk_i32 s4, 0x800
	s_mov_b32 s5, 0
	s_waitcnt lgkmcnt(0)
	v_readfirstlane_b32 s6, v1
	v_lshl_add_u64 v[0:1], v[156:157], 0, s[4:5]
	v_mov_b32_e32 v2, 1
	v_readlane_b32 s7, v254, 2
	s_nop 0
	s_cmp_eq_u32 s7, 2
	s_cselect_b32 s6, 0, s6
	s_cmp_eq_u32 s6, 0
	s_cbranch_scc1 .Lxq_slow_1
	global_atomic_add v3, v[0:1], v2, off sc0
	buffer_inv sc1
	s_mov_b32 s7, 0
	s_waitcnt vmcnt(0)
	v_or_b32_e32 v3, 3, v3
	v_add_u32_e32 v3, 1, v3

; DEVI unsigned xb_ld(unsigned* p)              { return __hip_atomic_load(p, __ATOMIC_RELAXED, __HIP_MEMORY_SCOPE_AGENT); }
; DEVI unsigned xb_add(unsigned* p, unsigned v) { return __hip_atomic_fetch_add(p, v, __ATOMIC_RELAXED, __HIP_MEMORY_SCOPE_AGENT); }
; #define XB_SPIN(cond, bar) do { unsigned _sp = 0; while (cond) { __builtin_amdgcn_s_sleep(1); \
;     if ((++_sp & 255u) == 0u) { if (xb_ld(&(bar)[XB_TMO])) break; if (_sp > XB_SPIN_CAP) { atomicAdd(&(bar)[XB_TMO], 1u); break; } } } } while (0)
; DEVI void xcd_barrier(const XcdBarrier& b) {
;     asm volatile("s_waitcnt vmcnt(0)" ::: "memory");
;     __syncthreads();
;     if (threadIdx.x == 0) {
;         unsigned* bar = b.bar;
;         __builtin_amdgcn_s_waitcnt(0);
;         unsigned nloc = b.st[0], nx = b.st[1];
;         if (nloc == 0u) { xcd_barrier_complete(bar, b.x, nloc, nx); b.st[0] = nloc; b.st[1] = nx; }
;         const unsigned old = xb_add(&bar[XB_XSUB(b.x)], 1u);
;         const unsigned gen = old / nloc;
;         if (old + 1u == (gen + 1u) * nloc) {
;             __builtin_amdgcn_fence(__ATOMIC_RELEASE, "agent");
;             asm volatile("s_waitcnt vmcnt(0)" ::: "memory");
;             const unsigned og = xb_add(&bar[XB_TOP], 1u);
;             const unsigned tg = og / nx;
;             if (og + 1u == (tg + 1u) * nx) xb_add(&bar[XB_TOPGEN], 1u);
;             else XB_SPIN(xb_ld(&bar[XB_TOPGEN]) == tg, bar);
;             __builtin_amdgcn_fence(__ATOMIC_ACQUIRE, "agent");
;             xb_add(&bar[XB_XGEN(b.x)], 1u);
;             asm volatile("s_waitcnt vmcnt(0)" ::: "memory");
;         } else {
;             XB_SPIN(xb_ld(&bar[XB_XGEN(b.x)]) == gen, bar);
;             __builtin_amdgcn_fence(__ATOMIC_ACQUIRE, "agent");
;             asm volatile("s_waitcnt vmcnt(0)" ::: "memory");
;         }
;     }
;     __syncthreads();
; }
.LBB0_1527:
	s_waitcnt vmcnt(0)
	s_barrier
	s_mov_b64 s[2:3], exec
	v_readlane_b32 s0, v251, 6
	v_readlane_b32 s1, v251, 7
	s_and_b64 s[0:1], s[2:3], s[0:1]
	s_mov_b64 exec, s[0:1]
	s_cbranch_execz .LBB0_1575
	v_mov_b32_e32 v1, 0x26008
	ds_read_b32 v1, v1
	s_bfe_u32 s4, s33, 0x30003
	s_lshl_b32 s4, s4, 5
	s_addk_i32 s4, 0x800
	s_mov_b32 s5, 0
	s_waitcnt lgkmcnt(0)
	v_readfirstlane_b32 s6, v1
	v_lshl_add_u64 v[0:1], v[156:157], 0, s[4:5]
	v_mov_b32_e32 v2, 1
	s_cmp_eq_u32 s6, 0
	s_cbranch_scc1 .Lxq_slow_2
	global_atomic_add v3, v[0:1], v2, off sc0
	buffer_inv sc1
	s_mov_b32 s7, 0
	s_waitcnt vmcnt(0)
	v_or_b32_e32 v3, 3, v3
	v_add_u32_e32 v3, 1, v3
